# gdn-prep D3/D4 inverse levels: MFMA operand reads hoisted ahead of the dependent MFMA chain (was one LDS round trip per MFMA); on top of D1/pk/DPP
# speedup vs baseline: 1.0052x; 1.0052x over previous
; #define LDS_BARRIER() asm volatile("s_waitcnt lgkmcnt(0)\n\ts_barrier" ::: "memory")
; __device__ __forceinline__ void gdn_prep_phase(const Frame& F0, const Args& a0, int l) {
;     ...
;             for (int lev = 1; lev <= 3; ++lev) {
;                 const int nb = 4 - lev;
;                 if (wave < 2 * nb) { const int d = wave / nb, bj = wave % nb, bi = bj + lev;
;                     f32x4 t = (f32x4){0.f, 0.f, 0.f, 0.f};
; #pragma unroll
;                     for (int k = 0; k < 3; ++k) if (k < lev) { const int bk = bj + k;
; #pragma unroll
;                         for (int s = 0; s < 4; ++s) t = __builtin_amdgcn_mfma_f32_16x16x4f32(GD_AEL(d, 16 * bi + cc, 16 * bk + 4 * s + g), GD_MEL(d, 16 * bk + 4 * s + g, 16 * bj + cc), t, 0, 0, 0); }
;                     f32x4 m2 = (f32x4){0.f, 0.f, 0.f, 0.f};
; #pragma unroll
;                     for (int s = 0; s < 4; ++s) m2 = __builtin_amdgcn_mfma_f32_16x16x4f32(GD_MEL(d, 16 * bi + cc, 16 * bi + 4 * g + s), t[s], m2, 0, 0, 0);
; #pragma unroll
;                     for (int r = 0; r < 4; ++r) GD_MEL(d, 16 * bi + 4 * g + r, 16 * bj + cc) = -m2[r];
;                 }
;                 LDS_BARRIER();
;             }
.LBB0_442:
	s_waitcnt lgkmcnt(0)
	s_barrier
	s_and_b64 vcc, exec, s[8:9]
	s_cbranch_vccnz .LBB0_444
	v_or_b32_e32 v22, s50, v109
	v_mul_lo_u32 v32, v22, s86
	v_readlane_b32 s10, v220, 44
	v_add_u32_e32 v22, s61, v110
	v_lshlrev_b32_e32 v23, 2, v22
	v_add_u32_e32 v34, s10, v20
	v_readlane_b32 s10, v220, 43
	s_nop 1
	v_add3_u32 v23, s10, v32, v23
	v_mad_u64_u32 v[26:27], s[10:11], v22, s86, v[34:35]
	v_add_u32_e32 v27, 0xcc00, v23
	v_add_u32_e32 v35, s50, v21
	ds_read_b32 v224, v26
	ds_read_b32 v225, v26 offset:1088
	ds_read_b32 v226, v26 offset:2176
	ds_read_b32 v227, v26 offset:3264
	ds_read_b32 v228, v26 offset:4352
	ds_read_b32 v229, v26 offset:5440
	ds_read_b32 v230, v26 offset:6528
	ds_read_b32 v231, v26 offset:7616
	ds_read2_b32 v[232:233], v27 offset1:4
	ds_read2_b32 v[234:235], v27 offset0:8 offset1:12
	ds_read2_b32 v[236:237], v27 offset0:16 offset1:20
	ds_read2_b32 v[238:239], v27 offset0:24 offset1:28
	s_waitcnt lgkmcnt(0)
	v_mfma_f32_16x16x4_f32 v[22:25], v232, v224, 0
	v_mfma_f32_16x16x4_f32 v[22:25], v233, v225, v[22:25]
	v_mfma_f32_16x16x4_f32 v[22:25], v234, v226, v[22:25]
	v_mfma_f32_16x16x4_f32 v[22:25], v235, v227, v[22:25]
	v_mfma_f32_16x16x4_f32 v[22:25], v236, v228, v[22:25]
	v_mfma_f32_16x16x4_f32 v[22:25], v237, v229, v[22:25]
	v_mfma_f32_16x16x4_f32 v[22:25], v238, v230, v[22:25]
	v_mfma_f32_16x16x4_f32 v[22:25], v239, v231, v[22:25]
	v_lshlrev_b32_e32 v26, 2, v35
	v_add3_u32 v26, s66, v32, v26
	ds_read_b128 v[26:29], v26
	s_waitcnt lgkmcnt(0)
	s_nop 5
	v_mfma_f32_16x16x4_f32 v[30:33], v26, v22, 0
	v_mfma_f32_16x16x4_f32 v[30:33], v27, v23, v[30:33]
	v_mad_u64_u32 v[26:27], s[10:11], v35, s86, v[34:35]
	v_mfma_f32_16x16x4_f32 v[30:33], v28, v24, v[30:33]
	v_mfma_f32_16x16x4_f32 v[22:25], v29, v25, v[30:33]
	s_nop 9
	v_xor_b32_e32 v22, 0x80000000, v22
	v_xor_b32_e32 v23, 0x80000000, v23
	ds_write2_b32 v26, v22, v23 offset1:68
	v_xor_b32_e32 v22, 0x80000000, v24
	v_xor_b32_e32 v23, 0x80000000, v25
	ds_write2_b32 v26, v22, v23 offset0:136 offset1:204
.LBB0_444:
	s_waitcnt lgkmcnt(0)
	s_barrier
	s_andn2_b64 vcc, exec, s[92:93]
	s_cbranch_vccnz .LBB0_446
	v_readlane_b32 s10, v220, 45
	v_add_u32_e32 v32, s47, v20
	s_nop 0
	v_mov_b32_e32 v22, s10
	v_mad_u32_u24 v22, v109, s86, v22
	v_add_u32_e32 v23, v22, v21
	v_mad_u64_u32 v[26:27], s[10:11], v110, s86, v[32:33]
	v_lshl_add_u32 v27, v110, 2, v22
	v_add_u32_e32 v30, 0xfc00, v27
	v_add_u32_e32 v33, 48, v21
	ds_read_b32 v252, v23 offset:65280
	ds_read_b32 v224, v26
	ds_read_b32 v225, v26 offset:1088
	ds_read_b32 v226, v26 offset:2176
	ds_read_b32 v227, v26 offset:3264
	ds_read_b32 v228, v26 offset:4352
	ds_read_b32 v229, v26 offset:5440
	ds_read2_b32 v[240:241], v30 offset0:196 offset1:200
	ds_read2_b32 v[242:243], v30 offset0:204 offset1:208
	ds_read2_b32 v[244:245], v30 offset0:212 offset1:216
	v_lshlrev_b32_e32 v21, 2, v33
	s_waitcnt lgkmcnt(0)
	ds_read_b32 v230, v26 offset:6528
	ds_read_b32 v231, v26 offset:7616
	ds_read_b32 v232, v26 offset:8704
	ds_read_b32 v233, v26 offset:9792
	ds_read_b32 v234, v26 offset:10880
	ds_read_b32 v235, v26 offset:11968
	ds_read2_b32 v[246:247], v30 offset0:220 offset1:224
	ds_read2_b32 v[248:249], v30 offset0:228 offset1:232
	ds_read_b32 v253, v27 offset:65456
	v_mfma_f32_16x16x4_f32 v[22:25], v252, v224, 0
	v_mfma_f32_16x16x4_f32 v[22:25], v240, v225, v[22:25]
	v_mfma_f32_16x16x4_f32 v[22:25], v241, v226, v[22:25]
	v_mfma_f32_16x16x4_f32 v[22:25], v242, v227, v[22:25]
	v_mfma_f32_16x16x4_f32 v[22:25], v243, v228, v[22:25]
	v_mfma_f32_16x16x4_f32 v[22:25], v244, v229, v[22:25]
	v_mul_u32_u24_e32 v27, 0x110, v109
	v_add3_u32 v27, s47, v27, v21
	s_waitcnt lgkmcnt(0)
	v_mfma_f32_16x16x4_f32 v[22:25], v245, v230, v[22:25]
	v_mfma_f32_16x16x4_f32 v[22:25], v246, v231, v[22:25]
	v_mfma_f32_16x16x4_f32 v[22:25], v247, v232, v[22:25]
	v_mfma_f32_16x16x4_f32 v[22:25], v248, v233, v[22:25]
	v_mfma_f32_16x16x4_f32 v[22:25], v249, v234, v[22:25]
	v_mfma_f32_16x16x4_f32 v[20:23], v253, v235, v[22:25]
	s_nop 3
	ds_read_b128 v[24:27], v27 offset:13056
	s_waitcnt lgkmcnt(0)
	s_nop 3
	v_mfma_f32_16x16x4_f32 v[28:31], v24, v20, 0
	v_mfma_f32_16x16x4_f32 v[28:31], v25, v21, v[28:31]
	v_mad_u64_u32 v[24:25], s[10:11], v33, s86, v[32:33]
	v_mfma_f32_16x16x4_f32 v[28:31], v26, v22, v[28:31]
	v_mfma_f32_16x16x4_f32 v[20:23], v27, v23, v[28:31]
	s_nop 9
	v_xor_b32_e32 v20, 0x80000000, v20
	v_xor_b32_e32 v21, 0x80000000, v21
	v_xor_b32_e32 v22, 0x80000000, v22
	v_xor_b32_e32 v23, 0x80000000, v23
	ds_write2_b32 v24, v20, v21 offset1:68
	ds_write2_b32 v24, v22, v23 offset0:136 offset1:204
